# P2: odd-lc workgroups run attention first and their pooling items afterwards (de-synchronise the pooling burst inside each team)
# speedup vs baseline: 1.0084x; 1.0018x over previous
.LBB0_343:
	s_or_b64 exec, exec, s[0:1]
	s_add_u32 s64, s50, 0x5000000
	s_addc_u32 s65, s51, 0
	v_readlane_b32 s0, v245, 0
	s_bitcmp1_b32 s0, 1
	s_waitcnt lgkmcnt(0)
	s_barrier
	s_cbranch_scc1 .LBB0_410
	s_bitcmp1_b32 s80, 0
	s_cbranch_scc1 .LBB0_410
.Lpool_body:
	v_mov_b32_e32 v3, v0
	v_mbcnt_lo_u32_b32 v2, -1, 0
	v_mbcnt_hi_u32_b32 v2, -1, v2
	s_nop 0
	v_readfirstlane_b32 s2, v3
	s_lshr_b32 s0, s2, 6
	s_add_i32 s1, s0, s53
	s_cmpk_gt_i32 s1, 0xff
	s_cbranch_scc1 .Lpool_exit
	s_bfe_u32 s4, s2, 0x20006
	s_lshl_b32 s5, s4, 8
	v_readlane_b32 s2, v245, 11
	v_and_b32_e32 v134, -16, v2
	s_add_u32 s2, s2, s5
	v_readlane_b32 s3, v245, 12
	v_lshlrev_b32_e32 v2, 4, v2
	s_addc_u32 s3, s3, 0
	v_and_b32_e32 v2, 0xf0, v2
	v_mov_b32_e32 v3, 0
	v_lshl_add_u64 v[126:127], s[2:3], 0, v[2:3]
	s_add_u32 s2, s64, s5
	s_addc_u32 s3, s65, 0
	s_add_i32 s5, s1, 0xffffff00
	s_lshl_b32 s1, s80, 7
	s_lshl_b32 s0, s0, 4
	v_lshl_add_u64 v[128:129], s[2:3], 0, v[2:3]
	s_add_i32 s6, s1, s0
	s_movk_i32 s7, 0x1000
	s_movk_i32 s8, 0x2000
	s_movk_i32 s9, 0x3000
	s_movk_i32 s10, 0x4000
	s_movk_i32 s11, 0x5000
	s_movk_i32 s12, 0x6000
	s_movk_i32 s13, 0x7000
	s_mov_b32 s14, 0x3d800000
	s_mov_b32 s15, 0x3e000000
	s_mov_b32 s16, 0x3e800000
	s_branch .LBB0_348

.Lpool_exit:
	s_bitcmp1_b32 s80, 0
	s_cbranch_scc1 .LBB0_519

.LBB0_518:
	v_readlane_b32 s76, v245, 19
	v_readlane_b32 s64, v245, 16
	v_readlane_b32 s66, v245, 14
	v_readlane_b32 s78, v245, 21
	v_readlane_b32 s79, v245, 22
	v_readlane_b32 s75, v245, 18
	v_readlane_b32 s80, v245, 32
	v_readlane_b32 s65, v245, 17
	v_readlane_b32 s67, v245, 15
	v_readlane_b32 s82, v245, 31
	v_readlane_b32 s77, v245, 20
	s_bitcmp1_b32 s80, 0
	s_cbranch_scc0 .LBB0_519
	s_lshl_b32 s53, s80, 3
	s_branch .Lpool_body
